# v13 plus out-proj epilogue: touch-prefetch of the next unit's residual tile lines (2 dword loads per wave)
# baseline (speedup 1.0000x reference)
;     __device__ __forceinline__ bool next(int i, pg8::Unit& u) const { if (i > 0) return false; u.pm = pm; u.pn = pn; return true; }
;     __host__ __device__ bool next(int i, Unit& u) const {
;         const long L = (long)i * G + c; if (L >= nwg) return false;
;         int wgid = (int)L; { const int q = nwg / NXCD, r = nwg % NXCD, xcd = wgid % NXCD, off = wgid / NXCD; wgid = (xcd < r ? xcd * (q + 1) : r * (q + 1) + (xcd - r) * q) + off; }
; __global__ void __launch_bounds__(NWAVES * 64, 2) hymba_fwd(Args args) {
;     ...
;     if (IN(5)) {
;         pg8::Gemm g{WSP(const pg8::bf16_t, WS_MIX), WSP(const pg8::bf16_t, WS_WOUT), MP, DM, DM}; pg8::StaticOrder S; S.init(MP, DM, F.G, (int)blockIdx.x);
;         EpiOut E{WSP(const bf16, WS_XB), F.out, F.lds + OSTAGE_OFF};
;         stagger_start((int)blockIdx.x, (MP / 256) * (DM / 256) % F.G, F.G, STAG3);
;         pg8::gemm_phase<EpiOut, pg8::StaticOrder, true, true>(F.lds + RING_OFF, g, S, E);
.LBB0_1218:
	v_readfirstlane_b32 s100, v0
	s_lshr_b32 s100, s100, 6
	s_cmp_lt_i32 s60, 6
	s_cselect_b64 s[0:1], -1, 0
	s_cmp_gt_i32 s61, 5
	s_cselect_b64 s[4:5], -1, 0
	s_and_b64 s[0:1], s[0:1], s[4:5]
	s_andn2_b64 vcc, exec, s[0:1]
	s_cbranch_vccnz .LBB0_1243
	s_cmpk_gt_i32 s2, 0x3ff
	v_readfirstlane_b32 s6, v0
	s_cbranch_scc1 .LBB0_1243
	s_ashr_i32 s28, s2, 31
	s_lshr_b32 s0, s28, 29
	s_add_i32 s7, s2, s0
	s_and_b32 s0, s7, -8
	s_sub_i32 s5, s2, s0
	s_cmp_gt_i32 s5, -1
	s_cbranch_scc0 .LBB0_1222
	s_lshl_b32 s4, s5, 7
	s_ashr_i32 s0, s7, 3
	s_cbranch_execz .LBB0_1223
	s_branch .LBB0_1224

; #define LAS __attribute__((address_space(3)))
; #define NTLD(p) __builtin_nontemporal_load(p)
;     __device__ __forceinline__ void operator()(const f32x4 (&acc)[2][2][4][2], const pg8::Unit& u, int wr, int wc, int fr, int fq) const {
;     ...
;         const int pm = u.pm; const bool sample = pm >= (MP / 256);
;         const bf16* xb = xbf + (size_t)pm * 256 * DM;
;         float* ob = sample ? out + OUT_YS + (size_t)(pm - MP / 256) * 256 * DM : out + OUT_YP + (size_t)pm * 256 * DM;
;         LAS unsigned char* T = stg + (wr * 4 + wc) * 2048;
;         const int lane = fr + 16 * fq, rr = lane >> 3, p = lane & 7;
;         const int woff0 = fr * 128 + ((fq ^ (fr & 7)) << 4), woff1 = fr * 128 + (((4 + fq) ^ (fr & 7)) << 4);
;         const int roff = rr * 128 + ((p ^ rr) << 4);
;         const int cb = 256 * u.pn + 32 * wc + 4 * p;
; #pragma unroll
;         for (int ai = 0; ai < 2; ++ai) {
;             v4u xv[4][2][2];
; #pragma unroll
;             for (int m = 0; m < 4; ++m) {
;                 const size_t ro = (size_t)(128 * ai + 64 * wr + 16 * m + rr) * DM + (cb & ~7);
; #pragma unroll
;                 for (int bj = 0; bj < 2; ++bj) { xv[m][bj][0] = NTLD((const v4u*)(xb + ro + 128 * bj)); xv[m][bj][1] = NTLD((const v4u*)(xb + ro + 8 * DM + 128 * bj)); }
;             }
; #pragma unroll
;             for (int m = 0; m < 4; ++m) {
;                 const size_t ro = (size_t)(128 * ai + 64 * wr + 16 * m + rr) * DM + cb;
; #pragma unroll
;                 for (int bj = 0; bj < 2; ++bj) {
;                     *(LAS f32x4*)(T + woff0) = acc[ai][bj][m][0]; *(LAS f32x4*)(T + woff1) = acc[ai][bj][m][1];
;                     const f32x4 a0 = *(const LAS f32x4*)(T + roff), a1 = *(const LAS f32x4*)(T + roff + 1024);
;                     const v4u t0 = xv[m][bj][0], t1 = xv[m][bj][1];
;                     const unsigned u0 = (p & 1) ? t0.z : t0.x, u1 = (p & 1) ? t0.w : t0.y, u2 = (p & 1) ? t1.z : t1.x, u3 = (p & 1) ? t1.w : t1.y;
;                     *(f32x4*)(ob + ro + 128 * bj) = (f32x4){bflo(u0), bfhi(u0), bflo(u1), bfhi(u1)} + a0; *(f32x4*)(ob + ro + 8 * DM + 128 * bj) = (f32x4){bflo(u2), bfhi(u2), bflo(u3), bfhi(u3)} + a1;
.LBB0_1239:
	s_add_i32 s6, s4, 0xffffff00
	s_ashr_i32 s5, s4, 31
	s_lshl_b64 s[22:23], s[6:7], 20
	s_add_u32 s6, s49, s22
	s_addc_u32 s15, s50, s23
	s_lshl_b64 s[22:23], s[4:5], 20
	s_add_u32 s17, s56, s22
	s_addc_u32 s22, s57, s23
	s_cmpk_gt_i32 s4, 0xff
	s_cselect_b32 s15, s15, s22
	s_cselect_b32 s6, s6, s17
	s_lshl_b64 s[4:5], s[4:5], 19
	v_mov_b32_e32 v134, v172
	v_mov_b32_e32 v135, v173
	s_add_u32 s4, s41, s4
	s_addc_u32 s5, s42, s5
	v_lshl_add_u32 v128, v135, 4, v134
	s_lshl_b32 s17, s58, 8
	v_ashrrev_i32_e32 v136, 3, v128
	v_and_b32_e32 v128, 7, v134
	s_or_b32 s17, s17, s44
	v_lshlrev_b32_e32 v137, 2, v128
	v_mov_b32_e32 v128, s17
	v_add_u32_e32 v166, s43, v136
	v_bitop3_b32 v128, v137, s54, v128 bitop3:0xc8
	v_ashrrev_i32_e32 v129, 31, v128
	v_ashrrev_i32_e32 v167, 31, v166
	v_lshl_add_u64 v[168:169], v[128:129], 1, s[4:5]
	v_lshlrev_b64 v[128:129], 11, v[166:167]
	v_lshl_add_u64 v[128:129], v[168:169], 0, v[128:129]
	global_load_dwordx4 v[182:185], v[128:129], off nt
	global_load_dwordx4 v[190:193], v[128:129], off offset:256 nt
	v_add_co_u32_e32 v130, vcc, s40, v128
	v_or_b32_e32 v128, s17, v137
	s_nop 0
	v_addc_co_u32_e32 v131, vcc, 0, v129, vcc
	global_load_dwordx4 v[186:189], v[130:131], off nt
	global_load_dwordx4 v[194:197], v[130:131], off offset:256 nt
	v_add_u32_e32 v222, 16, v166
	v_mov_b32_e32 v132, s6
	v_mov_b32_e32 v133, s15
	v_ashrrev_i32_e32 v129, 31, v128
	v_ashrrev_i32_e32 v223, 31, v222
	v_bitop3_b32 v138, v134, v135, 7 bitop3:0x6c
	v_add_u32_e32 v135, 4, v135
	v_lshl_add_u64 v[164:165], v[128:129], 2, v[132:133]
	v_lshlrev_b64 v[128:129], 11, v[222:223]
	v_bitop3_b32 v135, v135, v134, 7 bitop3:0x78
	v_lshl_add_u32 v130, v134, 7, s51
	v_lshl_add_u64 v[128:129], v[168:169], 0, v[128:129]
	v_lshl_add_u32 v179, v138, 4, v130
	v_lshl_add_u32 v180, v135, 4, v130
	v_add_co_u32_e32 v130, vcc, s40, v128
	v_add_u32_e32 v224, 32, v166
	s_nop 0
	v_addc_co_u32_e32 v131, vcc, 0, v129, vcc
	global_load_dwordx4 v[198:201], v[128:129], off nt
	global_load_dwordx4 v[202:205], v[128:129], off offset:256 nt
	global_load_dwordx4 v[206:209], v[130:131], off nt
	global_load_dwordx4 v[210:213], v[130:131], off offset:256 nt
	v_ashrrev_i32_e32 v225, 31, v224
	v_lshlrev_b64 v[128:129], 11, v[224:225]
	v_lshl_add_u64 v[128:129], v[168:169], 0, v[128:129]
	v_add_co_u32_e32 v130, vcc, s40, v128
	v_add_u32_e32 v170, 48, v166
	s_nop 0
	v_addc_co_u32_e32 v131, vcc, 0, v129, vcc
	global_load_dwordx4 v[214:217], v[128:129], off nt
	global_load_dwordx4 v[144:147], v[128:129], off offset:256 nt
	global_load_dwordx4 v[218:221], v[130:131], off nt
	global_load_dwordx4 v[148:151], v[130:131], off offset:256 nt
	v_ashrrev_i32_e32 v171, 31, v170
	v_lshlrev_b64 v[128:129], 11, v[170:171]
	v_lshl_add_u64 v[128:129], v[168:169], 0, v[128:129]
	v_lshlrev_b32_e32 v139, 7, v136
	v_bitop3_b32 v136, v136, v134, 7 bitop3:0x78
	v_add_co_u32_e32 v132, vcc, s40, v128
	v_lshlrev_b32_e32 v136, 4, v136
	s_nop 0
	v_addc_co_u32_e32 v133, vcc, 0, v129, vcc
	v_add3_u32 v178, s51, v139, v136
	v_and_b32_e32 v181, 1, v134
	global_load_dwordx4 v[136:139], v[128:129], off nt
	s_nop 0
	global_load_dwordx4 v[128:131], v[128:129], off offset:256 nt
	s_nop 0
	global_load_dwordx4 v[140:143], v[132:133], off nt
	s_nop 0
	global_load_dwordx4 v[132:135], v[132:133], off offset:256 nt
	s_and_b64 vcc, exec, s[0:1]
	s_cbranch_vccz .Lp3pf_skip
	s_lshl_b32 s98, s14, 19
	s_lshl_b32 s99, s16, 9
	s_add_u32 s98, s98, s99
	s_lshl_b32 s99, s100, 16
	s_add_u32 s98, s98, s99
	s_add_u32 s98, s41, s98
	s_addc_u32 s99, s42, 0
	v_mbcnt_lo_u32_b32 v247, -1, 0
	v_mbcnt_hi_u32_b32 v247, -1, v247
	v_and_b32_e32 v248, 3, v247
	v_lshrrev_b32_e32 v247, 2, v247
	v_lshlrev_b32_e32 v247, 11, v247
	v_lshl_or_b32 v247, v248, 7, v247
	v_add_u32_e32 v248, 0x8000, v247
	global_load_dword v249, v247, s[98:99]
	global_load_dword v249, v248, s[98:99]
.Lp3pf_skip:
	ds_write_b128 v179, v[124:127]
	ds_write_b128 v180, v[120:123]
	ds_read_b128 v[120:123], v178
	ds_read_b128 v[124:127], v178 offset:1024
	v_cmp_eq_u32_e32 vcc, 0, v181
	v_lshlrev_b64 v[226:227], 12, v[166:167]
	v_lshl_add_u64 v[226:227], v[164:165], 0, v[226:227]
	s_waitcnt vmcnt(0)
	v_cndmask_b32_e32 v167, v184, v182, vcc
	v_cndmask_b32_e32 v181, v185, v183, vcc
	v_lshlrev_b32_e32 v182, 16, v167
	v_and_b32_e32 v183, 0xffff0000, v167
	v_lshlrev_b32_e32 v184, 16, v181
	v_and_b32_e32 v185, 0xffff0000, v181
	s_waitcnt lgkmcnt(1)
	v_pk_add_f32 v[120:121], v[120:121], v[182:183]
	v_cndmask_b32_e32 v186, v188, v186, vcc
	v_pk_add_f32 v[122:123], v[122:123], v[184:185]
	v_cndmask_b32_e32 v187, v189, v187, vcc
	global_store_dwordx4 v[226:227], v[120:123], off
	s_nop 1
	v_lshlrev_b32_e32 v120, 16, v186
	v_and_b32_e32 v121, 0xffff0000, v186
	v_lshlrev_b32_e32 v122, 16, v187
	v_and_b32_e32 v123, 0xffff0000, v187
	s_waitcnt lgkmcnt(0)
	v_pk_add_f32 v[120:121], v[124:125], v[120:121]
	v_add_co_u32_e64 v124, s[4:5], s47, v226
	v_pk_add_f32 v[122:123], v[126:127], v[122:123]
	s_nop 0
	v_addc_co_u32_e64 v125, s[4:5], 0, v227, s[4:5]
	global_store_dwordx4 v[124:125], v[120:123], off
	ds_write_b128 v179, v[116:119]
	ds_write_b128 v180, v[112:115]
	ds_read_b128 v[112:115], v178
	ds_read_b128 v[116:119], v178 offset:1024
	v_cndmask_b32_e32 v121, v192, v190, vcc
	v_cndmask_b32_e32 v123, v193, v191, vcc
	v_lshlrev_b32_e32 v120, 16, v121
	v_and_b32_e32 v121, 0xffff0000, v121
	v_lshlrev_b32_e32 v122, 16, v123
	v_and_b32_e32 v123, 0xffff0000, v123
	v_cndmask_b32_e32 v126, v196, v194, vcc
	v_cndmask_b32_e32 v127, v197, v195, vcc
	s_waitcnt lgkmcnt(1)
; #define LAS __attribute__((address_space(3)))
;     __device__ __forceinline__ void operator()(const f32x4 (&acc)[2][2][4][2], const pg8::Unit& u, int wr, int wc, int fr, int fq) const {
;     ...
;             for (int m = 0; m < 4; ++m) {
;                 const size_t ro = (size_t)(128 * ai + 64 * wr + 16 * m + rr) * DM + cb;
; #pragma unroll
;                 for (int bj = 0; bj < 2; ++bj) {
;                     *(LAS f32x4*)(T + woff0) = acc[ai][bj][m][0]; *(LAS f32x4*)(T + woff1) = acc[ai][bj][m][1];
;                     const f32x4 a0 = *(const LAS f32x4*)(T + roff), a1 = *(const LAS f32x4*)(T + roff + 1024);
;                     const v4u t0 = xv[m][bj][0], t1 = xv[m][bj][1];
;                     const unsigned u0 = (p & 1) ? t0.z : t0.x, u1 = (p & 1) ? t0.w : t0.y, u2 = (p & 1) ? t1.z : t1.x, u3 = (p & 1) ? t1.w : t1.y;
;                     *(f32x4*)(ob + ro + 128 * bj) = (f32x4){bflo(u0), bfhi(u0), bflo(u1), bfhi(u1)} + a0; *(f32x4*)(ob + ro + 8 * DM + 128 * bj) = (f32x4){bflo(u2), bfhi(u2), bflo(u3), bfhi(u3)} + a1;
	v_pk_add_f32 v[112:113], v[112:113], v[120:121]
	v_pk_add_f32 v[114:115], v[114:115], v[122:123]
	global_store_dwordx4 v[226:227], v[112:115], off offset:512
	s_nop 1
	v_lshlrev_b32_e32 v112, 16, v126
	v_and_b32_e32 v113, 0xffff0000, v126
	v_lshlrev_b32_e32 v114, 16, v127
	v_and_b32_e32 v115, 0xffff0000, v127
	s_waitcnt lgkmcnt(0)
	v_pk_add_f32 v[112:113], v[116:117], v[112:113]
	v_pk_add_f32 v[114:115], v[118:119], v[114:115]
	global_store_dwordx4 v[124:125], v[112:115], off offset:512
	ds_write_b128 v179, v[108:111]
	ds_write_b128 v180, v[104:107]
	ds_read_b128 v[104:107], v178
	ds_read_b128 v[108:111], v178 offset:1024
	v_cndmask_b32_e32 v115, v200, v198, vcc
	v_cndmask_b32_e32 v117, v201, v199, vcc
	v_lshlrev_b64 v[112:113], 12, v[222:223]
	v_lshlrev_b32_e32 v114, 16, v115
	v_and_b32_e32 v115, 0xffff0000, v115
	v_lshlrev_b32_e32 v116, 16, v117
	v_and_b32_e32 v117, 0xffff0000, v117
	v_lshl_add_u64 v[112:113], v[164:165], 0, v[112:113]
	v_cndmask_b32_e32 v118, v208, v206, vcc
	s_waitcnt lgkmcnt(1)
	v_pk_add_f32 v[104:105], v[104:105], v[114:115]
	v_pk_add_f32 v[106:107], v[106:107], v[116:117]
	v_cndmask_b32_e32 v119, v209, v207, vcc
	global_store_dwordx4 v[112:113], v[104:107], off
	s_nop 1
	v_lshlrev_b32_e32 v104, 16, v118
	v_and_b32_e32 v105, 0xffff0000, v118
	v_lshlrev_b32_e32 v106, 16, v119
	v_and_b32_e32 v107, 0xffff0000, v119
	s_waitcnt lgkmcnt(0)
	v_pk_add_f32 v[104:105], v[108:109], v[104:105]
	v_add_co_u32_e64 v108, s[4:5], s47, v112
	v_pk_add_f32 v[106:107], v[110:111], v[106:107]
	s_nop 0
	v_addc_co_u32_e64 v109, s[4:5], 0, v113, s[4:5]
	global_store_dwordx4 v[108:109], v[104:107], off
	ds_write_b128 v179, v[100:103]
	ds_write_b128 v180, v[96:99]
	ds_read_b128 v[96:99], v178
	ds_read_b128 v[100:103], v178 offset:1024
	v_cndmask_b32_e32 v105, v204, v202, vcc
	v_cndmask_b32_e32 v107, v205, v203, vcc
	v_lshlrev_b32_e32 v104, 16, v105
	v_and_b32_e32 v105, 0xffff0000, v105
	v_lshlrev_b32_e32 v106, 16, v107
	v_and_b32_e32 v107, 0xffff0000, v107
	v_cndmask_b32_e32 v110, v212, v210, vcc
	v_cndmask_b32_e32 v111, v213, v211, vcc
	s_waitcnt lgkmcnt(1)
	v_pk_add_f32 v[96:97], v[96:97], v[104:105]
	v_pk_add_f32 v[98:99], v[98:99], v[106:107]
	global_store_dwordx4 v[112:113], v[96:99], off offset:512
	s_nop 1
	v_lshlrev_b32_e32 v96, 16, v110
	v_and_b32_e32 v97, 0xffff0000, v110
	v_lshlrev_b32_e32 v98, 16, v111
	v_and_b32_e32 v99, 0xffff0000, v111
	s_waitcnt lgkmcnt(0)
	v_pk_add_f32 v[96:97], v[100:101], v[96:97]
	v_pk_add_f32 v[98:99], v[102:103], v[98:99]
	global_store_dwordx4 v[108:109], v[96:99], off offset:512
	ds_write_b128 v179, v[92:95]
	ds_write_b128 v180, v[88:91]
	ds_read_b128 v[88:91], v178
	ds_read_b128 v[92:95], v178 offset:1024
	v_cndmask_b32_e32 v99, v216, v214, vcc
	v_cndmask_b32_e32 v101, v217, v215, vcc
	v_lshlrev_b64 v[96:97], 12, v[224:225]
	v_lshlrev_b32_e32 v98, 16, v99
	v_and_b32_e32 v99, 0xffff0000, v99
	v_lshlrev_b32_e32 v100, 16, v101
	v_and_b32_e32 v101, 0xffff0000, v101
	v_lshl_add_u64 v[96:97], v[164:165], 0, v[96:97]
	v_cndmask_b32_e32 v102, v220, v218, vcc
	s_waitcnt lgkmcnt(1)
	v_pk_add_f32 v[88:89], v[88:89], v[98:99]
	v_pk_add_f32 v[90:91], v[90:91], v[100:101]
	v_cndmask_b32_e32 v103, v221, v219, vcc
	global_store_dwordx4 v[96:97], v[88:91], off
	s_nop 1
	v_lshlrev_b32_e32 v88, 16, v102
	v_and_b32_e32 v89, 0xffff0000, v102
	v_lshlrev_b32_e32 v90, 16, v103
	v_and_b32_e32 v91, 0xffff0000, v103
	s_waitcnt lgkmcnt(0)
	v_pk_add_f32 v[88:89], v[92:93], v[88:89]
	v_add_co_u32_e64 v92, s[4:5], s47, v96
	v_pk_add_f32 v[90:91], v[94:95], v[90:91]
	s_nop 0
	v_addc_co_u32_e64 v93, s[4:5], 0, v97, s[4:5]
	global_store_dwordx4 v[92:93], v[88:91], off
	ds_write_b128 v179, v[84:87]
	ds_write_b128 v180, v[80:83]
	ds_read_b128 v[80:83], v178
	ds_read_b128 v[84:87], v178 offset:1024
	v_cndmask_b32_e32 v89, v146, v144, vcc
	v_cndmask_b32_e32 v91, v147, v145, vcc
	v_lshlrev_b32_e32 v88, 16, v89
	v_and_b32_e32 v89, 0xffff0000, v89
	v_lshlrev_b32_e32 v90, 16, v91
	v_and_b32_e32 v91, 0xffff0000, v91
	v_cndmask_b32_e32 v94, v150, v148, vcc
	v_cndmask_b32_e32 v95, v151, v149, vcc
	s_waitcnt lgkmcnt(1)
	v_pk_add_f32 v[80:81], v[80:81], v[88:89]
	v_pk_add_f32 v[82:83], v[82:83], v[90:91]
	global_store_dwordx4 v[96:97], v[80:83], off offset:512
	s_nop 1
	v_lshlrev_b32_e32 v80, 16, v94
	v_and_b32_e32 v81, 0xffff0000, v94
	v_lshlrev_b32_e32 v82, 16, v95
	v_and_b32_e32 v83, 0xffff0000, v95
	s_waitcnt lgkmcnt(0)
	v_pk_add_f32 v[80:81], v[84:85], v[80:81]
	v_pk_add_f32 v[82:83], v[86:87], v[82:83]
	global_store_dwordx4 v[92:93], v[80:83], off offset:512
	ds_write_b128 v179, v[76:79]
	ds_write_b128 v180, v[72:75]
	ds_read_b128 v[72:75], v178
	ds_read_b128 v[76:79], v178 offset:1024
	v_cndmask_b32_e32 v83, v138, v136, vcc
	v_cndmask_b32_e32 v85, v139, v137, vcc
	v_lshlrev_b64 v[80:81], 12, v[170:171]
	v_lshlrev_b32_e32 v82, 16, v83
	v_and_b32_e32 v83, 0xffff0000, v83
	v_lshlrev_b32_e32 v84, 16, v85
	v_and_b32_e32 v85, 0xffff0000, v85
	v_lshl_add_u64 v[80:81], v[164:165], 0, v[80:81]
	v_cndmask_b32_e32 v86, v142, v140, vcc
	s_waitcnt lgkmcnt(1)
	v_pk_add_f32 v[72:73], v[72:73], v[82:83]
	v_pk_add_f32 v[74:75], v[74:75], v[84:85]
	v_cndmask_b32_e32 v87, v143, v141, vcc
	global_store_dwordx4 v[80:81], v[72:75], off
	s_nop 1
	v_lshlrev_b32_e32 v72, 16, v86
	v_and_b32_e32 v73, 0xffff0000, v86
	v_lshlrev_b32_e32 v74, 16, v87
	v_and_b32_e32 v75, 0xffff0000, v87
	s_waitcnt lgkmcnt(0)
; #define LAS __attribute__((address_space(3)))
; #define NTLD(p) __builtin_nontemporal_load(p)
;     __device__ __forceinline__ void operator()(const f32x4 (&acc)[2][2][4][2], const pg8::Unit& u, int wr, int wc, int fr, int fq) const {
;     ...
;         for (int ai = 0; ai < 2; ++ai) {
;             v4u xv[4][2][2];
; #pragma unroll
;             for (int m = 0; m < 4; ++m) {
;                 const size_t ro = (size_t)(128 * ai + 64 * wr + 16 * m + rr) * DM + (cb & ~7);
; #pragma unroll
;                 for (int bj = 0; bj < 2; ++bj) { xv[m][bj][0] = NTLD((const v4u*)(xb + ro + 128 * bj)); xv[m][bj][1] = NTLD((const v4u*)(xb + ro + 8 * DM + 128 * bj)); }
;             }
; #pragma unroll
;             for (int m = 0; m < 4; ++m) {
;                 const size_t ro = (size_t)(128 * ai + 64 * wr + 16 * m + rr) * DM + cb;
; #pragma unroll
;                 for (int bj = 0; bj < 2; ++bj) {
;                     *(LAS f32x4*)(T + woff0) = acc[ai][bj][m][0]; *(LAS f32x4*)(T + woff1) = acc[ai][bj][m][1];
;                     const f32x4 a0 = *(const LAS f32x4*)(T + roff), a1 = *(const LAS f32x4*)(T + roff + 1024);
;                     const v4u t0 = xv[m][bj][0], t1 = xv[m][bj][1];
;                     const unsigned u0 = (p & 1) ? t0.z : t0.x, u1 = (p & 1) ? t0.w : t0.y, u2 = (p & 1) ? t1.z : t1.x, u3 = (p & 1) ? t1.w : t1.y;
;                     *(f32x4*)(ob + ro + 128 * bj) = (f32x4){bflo(u0), bfhi(u0), bflo(u1), bfhi(u1)} + a0; *(f32x4*)(ob + ro + 8 * DM + 128 * bj) = (f32x4){bflo(u2), bfhi(u2), bflo(u3), bfhi(u3)} + a1;
	v_pk_add_f32 v[72:73], v[76:77], v[72:73]
	v_add_co_u32_e64 v76, s[4:5], s47, v80
	v_pk_add_f32 v[74:75], v[78:79], v[74:75]
	s_nop 0
	v_addc_co_u32_e64 v77, s[4:5], 0, v81, s[4:5]
	global_store_dwordx4 v[76:77], v[72:75], off
	ds_write_b128 v179, v[68:71]
	ds_write_b128 v180, v[64:67]
	ds_read_b128 v[64:67], v178
	ds_read_b128 v[68:71], v178 offset:1024
	v_cndmask_b32_e32 v73, v130, v128, vcc
	v_cndmask_b32_e32 v75, v131, v129, vcc
	v_lshlrev_b32_e32 v72, 16, v73
	v_and_b32_e32 v73, 0xffff0000, v73
	v_lshlrev_b32_e32 v74, 16, v75
	v_and_b32_e32 v75, 0xffff0000, v75
	v_cndmask_b32_e32 v78, v134, v132, vcc
	v_cndmask_b32_e32 v79, v135, v133, vcc
	s_waitcnt lgkmcnt(1)
	v_pk_add_f32 v[64:65], v[64:65], v[72:73]
	v_pk_add_f32 v[66:67], v[66:67], v[74:75]
	global_store_dwordx4 v[80:81], v[64:67], off offset:512
	v_add_u32_e32 v130, 0x80, v166
	v_ashrrev_i32_e32 v131, 31, v130
	v_lshlrev_b32_e32 v64, 16, v78
	v_and_b32_e32 v65, 0xffff0000, v78
	v_lshlrev_b32_e32 v66, 16, v79
	v_and_b32_e32 v67, 0xffff0000, v79
	s_waitcnt lgkmcnt(0)
	v_pk_add_f32 v[64:65], v[68:69], v[64:65]
	v_pk_add_f32 v[66:67], v[70:71], v[66:67]
	global_store_dwordx4 v[76:77], v[64:67], off offset:512
	v_add_u32_e32 v132, 0x90, v166
	v_ashrrev_i32_e32 v133, 31, v132
	v_lshlrev_b64 v[64:65], 11, v[130:131]
	v_lshl_add_u64 v[64:65], v[168:169], 0, v[64:65]
	global_load_dwordx4 v[82:85], v[64:65], off nt
	v_add_co_u32_e64 v66, s[4:5], s40, v64
	v_add_u32_e32 v134, 0xa0, v166
	s_nop 0
	v_addc_co_u32_e64 v67, s[4:5], 0, v65, s[4:5]
	global_load_dwordx4 v[86:89], v[66:67], off nt
	global_load_dwordx4 v[90:93], v[64:65], off offset:256 nt
	global_load_dwordx4 v[94:97], v[66:67], off offset:256 nt
	v_lshlrev_b64 v[64:65], 11, v[132:133]
	v_lshl_add_u64 v[64:65], v[168:169], 0, v[64:65]
	v_add_co_u32_e64 v66, s[4:5], s40, v64
	v_ashrrev_i32_e32 v135, 31, v134
	s_nop 0
	v_addc_co_u32_e64 v67, s[4:5], 0, v65, s[4:5]
	global_load_dwordx4 v[98:101], v[64:65], off nt
	global_load_dwordx4 v[102:105], v[64:65], off offset:256 nt
	global_load_dwordx4 v[106:109], v[66:67], off nt
	global_load_dwordx4 v[110:113], v[66:67], off offset:256 nt
	v_lshlrev_b64 v[64:65], 11, v[134:135]
	v_lshl_add_u64 v[64:65], v[168:169], 0, v[64:65]
	v_add_co_u32_e64 v66, s[4:5], s40, v64
	v_add_u32_e32 v80, 0xb0, v166
	s_nop 0
	v_addc_co_u32_e64 v67, s[4:5], 0, v65, s[4:5]
	global_load_dwordx4 v[114:117], v[64:65], off nt
	global_load_dwordx4 v[118:121], v[64:65], off offset:256 nt
	global_load_dwordx4 v[122:125], v[66:67], off nt
	global_load_dwordx4 v[126:129], v[66:67], off offset:256 nt
	v_ashrrev_i32_e32 v81, 31, v80
	v_lshlrev_b64 v[64:65], 11, v[80:81]
	v_lshl_add_u64 v[64:65], v[168:169], 0, v[64:65]
	v_add_co_u32_e64 v68, s[4:5], s40, v64
	v_lshlrev_b64 v[130:131], 12, v[130:131]
	s_nop 0
	v_addc_co_u32_e64 v69, s[4:5], 0, v65, s[4:5]
	global_load_dwordx4 v[72:75], v[64:65], off nt
	s_nop 0
	global_load_dwordx4 v[64:67], v[64:65], off offset:256 nt
	s_nop 0
	global_load_dwordx4 v[76:79], v[68:69], off nt
	s_nop 0
	global_load_dwordx4 v[68:71], v[68:69], off offset:256 nt
	ds_write_b128 v179, v[60:63]
	ds_write_b128 v180, v[56:59]
	ds_read_b128 v[56:59], v178
	ds_read_b128 v[60:63], v178 offset:1024
	v_lshl_add_u64 v[130:131], v[164:165], 0, v[130:131]
	s_waitcnt vmcnt(15)
	v_cndmask_b32_e32 v84, v84, v82, vcc
	v_cndmask_b32_e32 v85, v85, v83, vcc
	v_lshlrev_b32_e32 v82, 16, v84
	v_and_b32_e32 v83, 0xffff0000, v84
	v_lshlrev_b32_e32 v84, 16, v85
	v_and_b32_e32 v85, 0xffff0000, v85
	s_waitcnt vmcnt(14)
	v_cndmask_b32_e32 v86, v88, v86, vcc
	s_waitcnt lgkmcnt(1)
	v_pk_add_f32 v[56:57], v[56:57], v[82:83]
	v_pk_add_f32 v[58:59], v[58:59], v[84:85]
	v_cndmask_b32_e32 v87, v89, v87, vcc
	global_store_dwordx4 v[130:131], v[56:59], off
	s_nop 1
	v_lshlrev_b32_e32 v56, 16, v86
	v_and_b32_e32 v57, 0xffff0000, v86
	v_lshlrev_b32_e32 v58, 16, v87
	v_and_b32_e32 v59, 0xffff0000, v87
	s_waitcnt lgkmcnt(0)
	v_pk_add_f32 v[56:57], v[60:61], v[56:57]
	v_add_co_u32_e64 v60, s[4:5], s47, v130
	v_pk_add_f32 v[58:59], v[62:63], v[58:59]
	s_nop 0
	v_addc_co_u32_e64 v61, s[4:5], 0, v131, s[4:5]
	global_store_dwordx4 v[60:61], v[56:59], off
	ds_write_b128 v179, v[52:55]
	ds_write_b128 v180, v[48:51]
	ds_read_b128 v[48:51], v178
	ds_read_b128 v[52:55], v178 offset:1024
	s_waitcnt vmcnt(15)
	v_cndmask_b32_e32 v57, v92, v90, vcc
	v_cndmask_b32_e32 v59, v93, v91, vcc
	v_lshlrev_b32_e32 v56, 16, v57
	v_and_b32_e32 v57, 0xffff0000, v57
	v_lshlrev_b32_e32 v58, 16, v59
	v_and_b32_e32 v59, 0xffff0000, v59
	s_waitcnt vmcnt(14)
	v_cndmask_b32_e32 v62, v96, v94, vcc
	v_cndmask_b32_e32 v63, v97, v95, vcc
	s_waitcnt lgkmcnt(1)
	v_pk_add_f32 v[48:49], v[48:49], v[56:57]
	v_pk_add_f32 v[50:51], v[50:51], v[58:59]
	global_store_dwordx4 v[130:131], v[48:51], off offset:512
	s_nop 1
	v_lshlrev_b32_e32 v48, 16, v62
	v_and_b32_e32 v49, 0xffff0000, v62
	v_lshlrev_b32_e32 v50, 16, v63
	v_and_b32_e32 v51, 0xffff0000, v63
	s_waitcnt lgkmcnt(0)
	v_pk_add_f32 v[48:49], v[52:53], v[48:49]
	v_pk_add_f32 v[50:51], v[54:55], v[50:51]
	global_store_dwordx4 v[60:61], v[48:51], off offset:512
	ds_write_b128 v179, v[44:47]
	ds_write_b128 v180, v[40:43]
	ds_read_b128 v[40:43], v178
	ds_read_b128 v[44:47], v178 offset:1024
	s_waitcnt vmcnt(15)
	v_cndmask_b32_e32 v51, v100, v98, vcc
	v_cndmask_b32_e32 v53, v101, v99, vcc
	v_lshlrev_b64 v[48:49], 12, v[132:133]
	v_lshlrev_b32_e32 v50, 16, v51
	v_and_b32_e32 v51, 0xffff0000, v51
	v_lshlrev_b32_e32 v52, 16, v53
	v_and_b32_e32 v53, 0xffff0000, v53
	v_lshl_add_u64 v[48:49], v[164:165], 0, v[48:49]
	s_waitcnt vmcnt(13)
	v_cndmask_b32_e32 v54, v108, v106, vcc
	s_waitcnt lgkmcnt(1)
; #define PG8_BAR __builtin_amdgcn_s_barrier()
; #define LAS __attribute__((address_space(3)))
; template <class Epi, class Sched, bool ALIGN_EPI = false, bool SP2 = false>
; __device__ __forceinline__ void gemm_phase(PG8_LAS unsigned char* lds, const Gemm g, const Sched& S, const Epi& E) {
;     ...
;         if constexpr (ALIGN_EPI) { if (wr == 0) PG8_BAR; }
;         if constexpr (!Epi::AFTER_DRAIN) { E(acc, cur, wr, wc, fr, fq); S.done(cur); }
;         if (!has_next) break;
; #pragma unroll
;         for (int a = 0; a < 2; ++a)
; #pragma unroll
;             for (int b = 0; b < 2; ++b)
; #pragma unroll
;                 for (int m = 0; m < 4; ++m)
; #pragma unroll
;                     for (int n = 0; n < 2; ++n) acc[a][b][m][n] = (f32x4){0.f, 0.f, 0.f, 0.f};
;         cur = nxt; cA = nA; cB = nB; ++ui;
;         if constexpr (ALIGN_EPI) { if (wr == 1) PG8_BAR; }
;     __device__ __forceinline__ void operator()(const f32x4 (&acc)[2][2][4][2], const pg8::Unit& u, int wr, int wc, int fr, int fq) const {
;     ...
;             for (int m = 0; m < 4; ++m) {
;                 const size_t ro = (size_t)(128 * ai + 64 * wr + 16 * m + rr) * DM + cb;
; #pragma unroll
;                 for (int bj = 0; bj < 2; ++bj) {
;                     *(LAS f32x4*)(T + woff0) = acc[ai][bj][m][0]; *(LAS f32x4*)(T + woff1) = acc[ai][bj][m][1];
;                     const f32x4 a0 = *(const LAS f32x4*)(T + roff), a1 = *(const LAS f32x4*)(T + roff + 1024);
;                     const v4u t0 = xv[m][bj][0], t1 = xv[m][bj][1];
;                     const unsigned u0 = (p & 1) ? t0.z : t0.x, u1 = (p & 1) ? t0.w : t0.y, u2 = (p & 1) ? t1.z : t1.x, u3 = (p & 1) ? t1.w : t1.y;
;                     *(f32x4*)(ob + ro + 128 * bj) = (f32x4){bflo(u0), bfhi(u0), bflo(u1), bfhi(u1)} + a0; *(f32x4*)(ob + ro + 8 * DM + 128 * bj) = (f32x4){bflo(u2), bfhi(u2), bflo(u3), bfhi(u3)} + a1;
	v_pk_add_f32 v[40:41], v[40:41], v[50:51]
	v_pk_add_f32 v[42:43], v[42:43], v[52:53]
	v_cndmask_b32_e32 v55, v109, v107, vcc
	global_store_dwordx4 v[48:49], v[40:43], off
	s_nop 1
	v_lshlrev_b32_e32 v40, 16, v54
	v_and_b32_e32 v41, 0xffff0000, v54
	v_lshlrev_b32_e32 v42, 16, v55
	v_and_b32_e32 v43, 0xffff0000, v55
	s_waitcnt lgkmcnt(0)
	v_pk_add_f32 v[40:41], v[44:45], v[40:41]
	v_add_co_u32_e64 v44, s[4:5], s47, v48
	v_pk_add_f32 v[42:43], v[46:47], v[42:43]
	s_nop 0
	v_addc_co_u32_e64 v45, s[4:5], 0, v49, s[4:5]
	global_store_dwordx4 v[44:45], v[40:43], off
	ds_write_b128 v179, v[36:39]
	ds_write_b128 v180, v[32:35]
	ds_read_b128 v[32:35], v178
	ds_read_b128 v[36:39], v178 offset:1024
	v_cndmask_b32_e32 v41, v104, v102, vcc
	v_cndmask_b32_e32 v43, v105, v103, vcc
	v_lshlrev_b32_e32 v40, 16, v41
	v_and_b32_e32 v41, 0xffff0000, v41
	v_lshlrev_b32_e32 v42, 16, v43
	v_and_b32_e32 v43, 0xffff0000, v43
	s_waitcnt vmcnt(14)
	v_cndmask_b32_e32 v46, v112, v110, vcc
	v_cndmask_b32_e32 v47, v113, v111, vcc
	s_waitcnt lgkmcnt(1)
	v_pk_add_f32 v[32:33], v[32:33], v[40:41]
	v_pk_add_f32 v[34:35], v[34:35], v[42:43]
	global_store_dwordx4 v[48:49], v[32:35], off offset:512
	s_nop 1
	v_lshlrev_b32_e32 v32, 16, v46
	v_and_b32_e32 v33, 0xffff0000, v46
	v_lshlrev_b32_e32 v34, 16, v47
	v_and_b32_e32 v35, 0xffff0000, v47
	s_waitcnt lgkmcnt(0)
	v_pk_add_f32 v[32:33], v[36:37], v[32:33]
	v_pk_add_f32 v[34:35], v[38:39], v[34:35]
	global_store_dwordx4 v[44:45], v[32:35], off offset:512
	ds_write_b128 v179, v[28:31]
	ds_write_b128 v180, v[24:27]
	ds_read_b128 v[24:27], v178
	ds_read_b128 v[28:31], v178 offset:1024
	s_waitcnt vmcnt(15)
	v_cndmask_b32_e32 v35, v116, v114, vcc
	v_cndmask_b32_e32 v37, v117, v115, vcc
	v_lshlrev_b64 v[32:33], 12, v[134:135]
	v_lshlrev_b32_e32 v34, 16, v35
	v_and_b32_e32 v35, 0xffff0000, v35
	v_lshlrev_b32_e32 v36, 16, v37
	v_and_b32_e32 v37, 0xffff0000, v37
	v_lshl_add_u64 v[32:33], v[164:165], 0, v[32:33]
	s_waitcnt vmcnt(13)
	v_cndmask_b32_e32 v38, v124, v122, vcc
	s_waitcnt lgkmcnt(1)
	v_pk_add_f32 v[24:25], v[24:25], v[34:35]
	v_pk_add_f32 v[26:27], v[26:27], v[36:37]
	v_cndmask_b32_e32 v39, v125, v123, vcc
	global_store_dwordx4 v[32:33], v[24:27], off
	s_nop 1
	v_lshlrev_b32_e32 v24, 16, v38
	v_and_b32_e32 v25, 0xffff0000, v38
	v_lshlrev_b32_e32 v26, 16, v39
	v_and_b32_e32 v27, 0xffff0000, v39
	s_waitcnt lgkmcnt(0)
	v_pk_add_f32 v[24:25], v[28:29], v[24:25]
	v_add_co_u32_e64 v28, s[4:5], s47, v32
	v_pk_add_f32 v[26:27], v[30:31], v[26:27]
	s_nop 0
	v_addc_co_u32_e64 v29, s[4:5], 0, v33, s[4:5]
	global_store_dwordx4 v[28:29], v[24:27], off
	ds_write_b128 v179, v[20:23]
	ds_write_b128 v180, v[16:19]
	ds_read_b128 v[16:19], v178
	ds_read_b128 v[20:23], v178 offset:1024
	v_cndmask_b32_e32 v25, v120, v118, vcc
	v_cndmask_b32_e32 v27, v121, v119, vcc
	v_lshlrev_b32_e32 v24, 16, v25
	v_and_b32_e32 v25, 0xffff0000, v25
	v_lshlrev_b32_e32 v26, 16, v27
	v_and_b32_e32 v27, 0xffff0000, v27
	s_waitcnt vmcnt(14)
	v_cndmask_b32_e32 v30, v128, v126, vcc
	v_cndmask_b32_e32 v31, v129, v127, vcc
	s_waitcnt lgkmcnt(1)
	v_pk_add_f32 v[16:17], v[16:17], v[24:25]
	v_pk_add_f32 v[18:19], v[18:19], v[26:27]
	global_store_dwordx4 v[32:33], v[16:19], off offset:512
	s_nop 1
	v_lshlrev_b32_e32 v16, 16, v30
	v_and_b32_e32 v17, 0xffff0000, v30
	v_lshlrev_b32_e32 v18, 16, v31
	v_and_b32_e32 v19, 0xffff0000, v31
	s_waitcnt lgkmcnt(0)
	v_pk_add_f32 v[16:17], v[20:21], v[16:17]
	v_pk_add_f32 v[18:19], v[22:23], v[18:19]
	global_store_dwordx4 v[28:29], v[16:19], off offset:512
	ds_write_b128 v179, v[12:15]
	ds_write_b128 v180, v[8:11]
	ds_read_b128 v[8:11], v178
	ds_read_b128 v[12:15], v178 offset:1024
	s_waitcnt vmcnt(15)
	v_cndmask_b32_e32 v19, v74, v72, vcc
	v_cndmask_b32_e32 v21, v75, v73, vcc
	v_lshlrev_b64 v[16:17], 12, v[80:81]
	v_lshlrev_b32_e32 v18, 16, v19
	v_and_b32_e32 v19, 0xffff0000, v19
	v_lshlrev_b32_e32 v20, 16, v21
	v_and_b32_e32 v21, 0xffff0000, v21
	v_lshl_add_u64 v[16:17], v[164:165], 0, v[16:17]
	s_waitcnt vmcnt(13)
	v_cndmask_b32_e32 v22, v78, v76, vcc
	s_waitcnt lgkmcnt(1)
	v_pk_add_f32 v[8:9], v[8:9], v[18:19]
	v_pk_add_f32 v[10:11], v[10:11], v[20:21]
	v_cndmask_b32_e32 v23, v79, v77, vcc
	global_store_dwordx4 v[16:17], v[8:11], off
	s_nop 1
	v_lshlrev_b32_e32 v8, 16, v22
	v_and_b32_e32 v9, 0xffff0000, v22
	v_lshlrev_b32_e32 v10, 16, v23
	v_and_b32_e32 v11, 0xffff0000, v23
	s_waitcnt lgkmcnt(0)
	v_pk_add_f32 v[8:9], v[12:13], v[8:9]
	v_add_co_u32_e64 v12, s[4:5], s47, v16
	v_pk_add_f32 v[10:11], v[14:15], v[10:11]
	s_nop 0
	v_addc_co_u32_e64 v13, s[4:5], 0, v17, s[4:5]
	global_store_dwordx4 v[12:13], v[8:11], off
	ds_write_b128 v179, v[4:7]
	ds_write_b128 v180, v[0:3]
	ds_read_b128 v[0:3], v178
	ds_read_b128 v[4:7], v178 offset:1024
	v_cndmask_b32_e32 v9, v66, v64, vcc
	v_cndmask_b32_e32 v11, v67, v65, vcc
	v_lshlrev_b32_e32 v8, 16, v9
	v_and_b32_e32 v9, 0xffff0000, v9
	v_lshlrev_b32_e32 v10, 16, v11
	v_and_b32_e32 v11, 0xffff0000, v11
	s_waitcnt vmcnt(14)
	v_cndmask_b32_e32 v14, v70, v68, vcc
	v_cndmask_b32_e32 v15, v71, v69, vcc
	s_waitcnt lgkmcnt(1)
	v_pk_add_f32 v[0:1], v[0:1], v[8:9]
	v_pk_add_f32 v[2:3], v[2:3], v[10:11]
	global_store_dwordx4 v[16:17], v[0:3], off offset:512
	s_andn2_b64 vcc, exec, s[0:1]
	s_mov_b64 s[0:1], -1
	v_lshlrev_b32_e32 v0, 16, v14
	v_and_b32_e32 v1, 0xffff0000, v14
	v_lshlrev_b32_e32 v2, 16, v15
	v_and_b32_e32 v3, 0xffff0000, v15
	s_waitcnt lgkmcnt(0)
	v_pk_add_f32 v[0:1], v[4:5], v[0:1]
	v_pk_add_f32 v[2:3], v[6:7], v[2:3]
	global_store_dwordx4 v[12:13], v[0:3], off offset:512
	s_cbranch_vccnz .LBB0_1228
	s_andn2_b64 vcc, exec, s[8:9]
	s_cbranch_vccnz .LBB0_1227
	s_barrier
	s_branch .LBB0_1227

; __global__ void __launch_bounds__(NWAVES * 64, 2) hymba_fwd(Args args) {
;     extern __shared__ __attribute__((aligned(16))) unsigned char lds[];
	.amdhsa_kernel _Z9hymba_fwd4Args
		.amdhsa_group_segment_fixed_size 0
		.amdhsa_private_segment_fixed_size 0
		.amdhsa_kernarg_size 392
		.amdhsa_user_sgpr_count 2
		.amdhsa_user_sgpr_dispatch_ptr 0
		.amdhsa_user_sgpr_queue_ptr 0
		.amdhsa_user_sgpr_kernarg_segment_ptr 1
		.amdhsa_user_sgpr_dispatch_id 0
		.amdhsa_user_sgpr_kernarg_preload_length 0
		.amdhsa_user_sgpr_kernarg_preload_offset 0
		.amdhsa_user_sgpr_private_segment_size 0
		.amdhsa_uses_dynamic_stack 0
		.amdhsa_enable_private_segment 0
		.amdhsa_system_sgpr_workgroup_id_x 1
		.amdhsa_system_sgpr_workgroup_id_y 0
		.amdhsa_system_sgpr_workgroup_id_z 0
		.amdhsa_system_sgpr_workgroup_info 0
		.amdhsa_system_vgpr_workitem_id 0
		.amdhsa_next_free_vgpr 250
		.amdhsa_next_free_sgpr 102
		.amdhsa_accum_offset 252
		.amdhsa_reserve_vcc 1
		.amdhsa_float_round_mode_32 0
		.amdhsa_float_round_mode_16_64 0
		.amdhsa_float_denorm_mode_32 3
		.amdhsa_float_denorm_mode_16_64 3
		.amdhsa_dx10_clamp 1
		.amdhsa_ieee_mode 1
		.amdhsa_fp16_overflow 0
		.amdhsa_tg_split 0
		.amdhsa_exception_fp_ieee_invalid_op 0
		.amdhsa_exception_fp_denorm_src 0
		.amdhsa_exception_fp_ieee_div_zero 0
		.amdhsa_exception_fp_ieee_overflow 0
		.amdhsa_exception_fp_ieee_underflow 0
		.amdhsa_exception_fp_ieee_inexact 0
		.amdhsa_exception_int_div_zero 0
	.end_amdhsa_kernel

; __global__ void __launch_bounds__(NWAVES * 64, 2) hymba_fwd(Args args) {
;     extern __shared__ __attribute__((aligned(16))) unsigned char lds[];
amdhsa.kernels:
  - .agpr_count:     0
    .args:
      - .offset:         0
        .size:           136
        .value_kind:     by_value
      - .offset:         136
        .size:           4
        .value_kind:     hidden_block_count_x
      - .offset:         140
        .size:           4
        .value_kind:     hidden_block_count_y
      - .offset:         144
        .size:           4
        .value_kind:     hidden_block_count_z
      - .offset:         148
        .size:           2
        .value_kind:     hidden_group_size_x
      - .offset:         150
        .size:           2
        .value_kind:     hidden_group_size_y
      - .offset:         152
        .size:           2
        .value_kind:     hidden_group_size_z
      - .offset:         154
        .size:           2
        .value_kind:     hidden_remainder_x
      - .offset:         156
        .size:           2
        .value_kind:     hidden_remainder_y
      - .offset:         158
        .size:           2
        .value_kind:     hidden_remainder_z
      - .offset:         176
        .size:           8
        .value_kind:     hidden_global_offset_x
      - .offset:         184
        .size:           8
        .value_kind:     hidden_global_offset_y
      - .offset:         192
        .size:           8
        .value_kind:     hidden_global_offset_z
      - .offset:         200
        .size:           2
        .value_kind:     hidden_grid_dims
      - .offset:         256
        .size:           4
        .value_kind:     hidden_dynamic_lds_size
    .group_segment_fixed_size: 0
    .kernarg_segment_align: 8
    .kernarg_segment_size: 392
    .language:       OpenCL C
    .language_version:
      - 2
      - 0
    .max_flat_workgroup_size: 512
    .name:           _Z9hymba_fwd4Args
    .private_segment_fixed_size: 0
    .sgpr_count:     108
    .sgpr_spill_count: 112
    .symbol:         _Z9hymba_fwd4Args.kd
    .uniform_work_group_size: 1
    .uses_dynamic_stack: false
    .vgpr_count:     250
    .vgpr_spill_count: 0
    .wavefront_size: 64
